# X unit: hand-written gated short conv with all taps loaded up front (no serialized exec-masked loads); on top of S queue prefetch
# baseline (speedup 1.0000x reference)
; DI v2u pack4(f32x4 a) { v2u w; w.x = cvtpk(a[0], a[1]); w.y = cvtpk(a[2], a[3]); return w; }
; DI f32x4 unpack4(v2u w) { return (f32x4){bflo(w.x), bfhi(w.x), bflo(w.y), bfhi(w.y)}; }
; DI void unit_memattn(int u, const bf16* __restrict__ MQ, const bf16* __restrict__ MK, const bf16* __restrict__ MV, const bf16* __restrict__ G, bf16* __restrict__ MIX, const bf16* __restrict__ CB, const bf16* __restrict__ U, const float* __restrict__ convw, ...
;     ...
;     const int b = u >> 7, hm = (u >> 5) & 3, qb = u & 31;
;     const long goff0 = ((long)b * 256) * 256 + hm * 64;
;     v4u fk[4], fv[4], gv[4];
; #pragma unroll
;     for (int i = 0; i < 4; ++i) { const int id = tid + NT * i, j = id >> 3, ch = id & 7;
;         fk[i] = *(const v4u*)(MK + goff0 + (long)j * 256 + ch * 8); fv[i] = *(const v4u*)(MV + goff0 + (long)j * 256 + ch * 8);
;         gv[i] = *(const v4u*)(G + ((size_t)b * SEQ + qb * 256 + j) * D + 768 + hm * 64 + ch * 8); }
;     {   const int c4 = hm * 64 + (tid & 15) * 4;
;         const f32x4 w0 = *(const f32x4*)(convw + c4), w1 = *(const f32x4*)(convw + 256 + c4), w2 = *(const f32x4*)(convw + 512 + c4);
; #pragma unroll 4
;         for (int rl = tid >> 4; rl < 256; rl += NT / 16) { const size_t r2 = (size_t)b * SEQ + qb * 256 + rl; const int t = (int)(r2 & (SEQ - 1));
;             const f32x4 cb = unpack4(*(const v2u*)(CB + r2 * 256 + c4)), u0 = unpack4(*(const v2u*)(U + r2 * 256 + c4));
;             f32x4 u1 = (f32x4){0.f, 0.f, 0.f, 0.f}, u2 = u1;
;             if (t >= 1) u1 = unpack4(*(const v2u*)(U + (r2 - 1) * 256 + c4));
;             if (t >= 2) u2 = unpack4(*(const v2u*)(U + (r2 - 2) * 256 + c4));
;             const f32x4 gg = unpack4(*(const v2u*)(G + r2 * D + c4));
;             *(v2u*)(MIX + r2 * D + c4) = pack4(cb * (w0 * u2 + w1 * u1 + w2 * u0) * gg); }
.LBB0_794:
	s_or_b64 exec, exec, s[0:1]
	s_waitcnt lgkmcnt(0)
	s_barrier
	ds_read_b32 v2, v152
	s_mov_b64 s[0:1], -1
	s_waitcnt lgkmcnt(0)
	v_readfirstlane_b32 s3, v2
	s_cmpk_gt_i32 s3, 0xff
	s_cbranch_scc1 .LBB0_789
	s_ashr_i32 s14, s3, 7
	s_lshl_b32 s0, s3, 1
	s_ashr_i32 s15, s14, 31
	s_and_b32 s2, s0, 0xc0
	s_lshl_b64 s[0:1], s[14:15], 17
	s_lshl_b32 s6, s2, 1
	s_or_b32 s0, s0, s6
	v_mov_b32_e32 v153, v0
	v_mov_b32_e32 v154, v182
	s_add_u32 s16, s55, s0
	s_addc_u32 s17, s46, s1
	v_lshlrev_b32_e32 v2, 3, v153
	v_and_b32_e32 v2, 56, v2
	s_add_u32 s0, s47, s0
	v_lshlrev_b32_e32 v132, 1, v2
	v_mov_b32_e32 v133, v3
	s_addc_u32 s1, s48, s1
	s_lshl_b32 s3, s3, 8
	v_lshl_add_u64 v[32:33], s[0:1], 0, v[132:133]
	s_lshl_b64 s[0:1], s[14:15], 13
	s_and_b32 s15, s3, 0x1f00
	v_ashrrev_i32_e32 v142, 3, v153
	v_lshl_add_u64 v[28:29], s[16:17], 0, v[132:133]
	s_or_b32 s16, s0, s15
	s_mov_b32 s17, s1
	v_ashrrev_i32_e32 v143, 31, v142
	v_lshlrev_b64 v[4:5], 9, v[142:143]
	v_lshl_add_u64 v[12:13], s[16:17], 0, v[142:143]
	v_add_u32_e32 v143, 0x200, v153
	v_ashrrev_i32_e32 v144, 3, v143
	v_ashrrev_i32_e32 v145, 31, v144
	v_lshl_add_u64 v[18:19], s[16:17], 0, v[144:145]
	v_lshlrev_b64 v[140:141], 11, v[12:13]
	v_lshlrev_b64 v[138:139], 11, v[18:19]
	v_lshl_add_u64 v[12:13], s[24:25], 0, v[140:141]
	v_lshlrev_b64 v[16:17], 9, v[144:145]
	v_lshl_add_u64 v[18:19], s[24:25], 0, v[138:139]
	v_add_u32_e32 v145, 0x400, v153
	v_lshl_add_u64 v[12:13], v[12:13], 0, s[6:7]
	v_lshl_add_u64 v[18:19], v[18:19], 0, s[6:7]
	v_ashrrev_i32_e32 v146, 3, v145
	v_lshl_add_u64 v[6:7], v[28:29], 0, v[4:5]
	v_lshl_add_u64 v[8:9], v[32:33], 0, v[4:5]
	v_lshl_add_u64 v[12:13], v[12:13], 0, v[132:133]
	v_lshl_add_u64 v[14:15], v[28:29], 0, v[16:17]
	v_lshl_add_u64 v[16:17], v[32:33], 0, v[16:17]
	v_lshl_add_u64 v[20:21], v[18:19], 0, v[132:133]
	v_ashrrev_i32_e32 v147, 31, v146
	global_load_dwordx4 v[4:7], v[6:7], off
	s_nop 0
	global_load_dwordx4 v[8:11], v[8:9], off
	s_nop 0
	global_load_dwordx4 v[80:83], v[12:13], off offset:1536
	s_nop 0
	global_load_dwordx4 v[12:15], v[14:15], off
	s_nop 0
	global_load_dwordx4 v[16:19], v[16:17], off
	s_nop 0
	global_load_dwordx4 v[76:79], v[20:21], off offset:1536
	v_lshlrev_b64 v[20:21], 9, v[146:147]
	v_lshl_add_u64 v[30:31], s[16:17], 0, v[146:147]
	v_add_u32_e32 v147, 0x600, v153
	v_ashrrev_i32_e32 v148, 3, v147
	v_ashrrev_i32_e32 v149, 31, v148
	v_lshlrev_b64 v[34:35], 9, v[148:149]
	v_lshl_add_u64 v[22:23], v[28:29], 0, v[20:21]
	v_lshl_add_u64 v[24:25], v[32:33], 0, v[20:21]
	v_lshlrev_b64 v[136:137], 11, v[30:31]
	v_lshl_add_u64 v[28:29], v[28:29], 0, v[34:35]
	v_lshl_add_u64 v[32:33], v[32:33], 0, v[34:35]
	v_lshl_add_u64 v[34:35], s[16:17], 0, v[148:149]
	v_lshl_add_u64 v[30:31], s[24:25], 0, v[136:137]
	v_lshlrev_b64 v[134:135], 11, v[34:35]
	v_lshl_add_u64 v[30:31], v[30:31], 0, s[6:7]
	v_lshl_add_u64 v[34:35], s[24:25], 0, v[134:135]
	v_lshl_add_u64 v[30:31], v[30:31], 0, v[132:133]
	v_lshl_add_u64 v[34:35], v[34:35], 0, s[6:7]
	global_load_dwordx4 v[20:23], v[22:23], off
	s_nop 0
	global_load_dwordx4 v[24:27], v[24:25], off
	s_nop 0
	global_load_dwordx4 v[72:75], v[30:31], off offset:1536
	s_nop 0
	global_load_dwordx4 v[28:31], v[28:29], off
	v_lshl_add_u64 v[36:37], v[34:35], 0, v[132:133]
	global_load_dwordx4 v[32:35], v[32:33], off
	s_nop 0
	global_load_dwordx4 v[68:71], v[36:37], off offset:1536
	v_ashrrev_i32_e32 v60, 4, v153
	v_cmp_gt_i32_e32 vcc, s28, v60
	s_and_saveexec_b64 s[16:17], vcc
	s_cbranch_execz .LBB0_823
	v_lshlrev_b32_e32 v2, 2, v153
	v_and_or_b32 v2, v2, 60, s2
	v_lshlrev_b32_e32 v104, 2, v2
	global_load_dwordx4 v[36:39], v104, s[68:69]
	global_load_dwordx4 v[40:43], v104, s[68:69] offset:1024
	global_load_dwordx4 v[44:47], v104, s[68:69] offset:2048
	s_lshl_b32 s43, s14, 13
	s_or_b32 s43, s43, s15
	s_lshl_b32 s0, s43, 9
	s_add_u32 s0, s0, 0x3400000
	s_add_u32 s0, s82, s0
	s_addc_u32 s1, s83, 0
	s_add_u32 s2, s0, 0xa00000
	s_addc_u32 s3, s1, 0
	s_lshl_b32 s18, s43, 11
	s_add_u32 s18, s18, 0x8800000
	s_add_u32 s18, s82, s18
	s_addc_u32 s19, s83, 0
	s_add_u32 s20, s18, 0x5800000
	s_addc_u32 s21, s19, 0
	v_lshlrev_b32_e32 v2, 1, v2
	v_add_u32_e32 v107, s15, v60
	v_lshl_add_u32 v104, v60, 9, v2
	v_lshl_add_u32 v105, v60, 11, v2
	v_mov_b32_e32 v106, v105
	global_load_dwordx2 v[48:49], v104, s[0:1]
	global_load_dwordx2 v[50:51], v104, s[2:3]
	global_load_dwordx2 v[52:53], v104, s[2:3] offset:-512
	global_load_dwordx2 v[54:55], v104, s[2:3] offset:-1024
	global_load_dwordx2 v[56:57], v105, s[18:19]
	v_add_u32_e32 v104, 0x4000, v104
	v_add_u32_e32 v105, 0x10000, v105
	global_load_dwordx2 v[58:59], v104, s[0:1]
	global_load_dwordx2 v[60:61], v104, s[2:3]
	global_load_dwordx2 v[62:63], v104, s[2:3] offset:-512
	global_load_dwordx2 v[64:65], v104, s[2:3] offset:-1024
	global_load_dwordx2 v[66:67], v105, s[18:19]
	v_add_u32_e32 v104, 0x4000, v104
	v_add_u32_e32 v105, 0x10000, v105
	global_load_dwordx2 v[84:85], v104, s[0:1]
	global_load_dwordx2 v[86:87], v104, s[2:3]
	global_load_dwordx2 v[88:89], v104, s[2:3] offset:-512
	global_load_dwordx2 v[90:91], v104, s[2:3] offset:-1024
	global_load_dwordx2 v[92:93], v105, s[18:19]
	v_add_u32_e32 v104, 0x4000, v104
	v_add_u32_e32 v105, 0x10000, v105
	global_load_dwordx2 v[94:95], v104, s[0:1]
	global_load_dwordx2 v[96:97], v104, s[2:3]
	global_load_dwordx2 v[98:99], v104, s[2:3] offset:-512
	global_load_dwordx2 v[100:101], v104, s[2:3] offset:-1024
	global_load_dwordx2 v[102:103], v105, s[18:19]
	v_add_u32_e32 v104, 0x4000, v104
	v_add_u32_e32 v105, 0x10000, v105
	s_waitcnt vmcnt(15)
; DI v2u pack4(f32x4 a) { v2u w; w.x = cvtpk(a[0], a[1]); w.y = cvtpk(a[2], a[3]); return w; }
; DI f32x4 unpack4(v2u w) { return (f32x4){bflo(w.x), bfhi(w.x), bflo(w.y), bfhi(w.y)}; }
; DI void unit_memattn(int u, const bf16* __restrict__ MQ, const bf16* __restrict__ MK, const bf16* __restrict__ MV, const bf16* __restrict__ G, bf16* __restrict__ MIX, const bf16* __restrict__ CB, const bf16* __restrict__ U, const float* __restrict__ convw, ...
;     ...
;         for (int rl = tid >> 4; rl < 256; rl += NT / 16) { const size_t r2 = (size_t)b * SEQ + qb * 256 + rl; const int t = (int)(r2 & (SEQ - 1));
;             const f32x4 cb = unpack4(*(const v2u*)(CB + r2 * 256 + c4)), u0 = unpack4(*(const v2u*)(U + r2 * 256 + c4));
;             f32x4 u1 = (f32x4){0.f, 0.f, 0.f, 0.f}, u2 = u1;
;             if (t >= 1) u1 = unpack4(*(const v2u*)(U + (r2 - 1) * 256 + c4));
;             if (t >= 2) u2 = unpack4(*(const v2u*)(U + (r2 - 2) * 256 + c4));
;             const f32x4 gg = unpack4(*(const v2u*)(G + r2 * D + c4));
;             *(v2u*)(MIX + r2 * D + c4) = pack4(cb * (w0 * u2 + w1 * u1 + w2 * u0) * gg); }
	v_cmp_ne_u32_e32 vcc, 0, v107
	s_nop 1
	v_cndmask_b32_e32 v52, v3, v52, vcc
	v_cndmask_b32_e32 v53, v3, v53, vcc
	v_cmp_lt_u32_e32 vcc, 1, v107
	s_nop 1
	v_cndmask_b32_e32 v54, v3, v54, vcc
	v_cndmask_b32_e32 v55, v3, v55, vcc
	v_lshlrev_b32_e32 v108, 16, v54
	v_and_b32_e32 v109, 0xffff0000, v54
	v_lshlrev_b32_e32 v110, 16, v55
	v_and_b32_e32 v111, 0xffff0000, v55
	v_pk_mul_f32 v[114:115], v[38:39], v[110:111]
	v_pk_mul_f32 v[112:113], v[36:37], v[108:109]
	v_lshlrev_b32_e32 v108, 16, v52
	v_and_b32_e32 v109, 0xffff0000, v52
	v_lshlrev_b32_e32 v110, 16, v53
	v_and_b32_e32 v111, 0xffff0000, v53
	v_pk_fma_f32 v[112:113], v[40:41], v[108:109], v[112:113]
	v_pk_fma_f32 v[114:115], v[42:43], v[110:111], v[114:115]
	v_lshlrev_b32_e32 v108, 16, v50
	v_and_b32_e32 v109, 0xffff0000, v50
	v_lshlrev_b32_e32 v110, 16, v51
	v_and_b32_e32 v111, 0xffff0000, v51
	v_pk_fma_f32 v[114:115], v[46:47], v[110:111], v[114:115]
	v_pk_fma_f32 v[112:113], v[44:45], v[108:109], v[112:113]
	v_lshlrev_b32_e32 v108, 16, v48
	v_and_b32_e32 v109, 0xffff0000, v48
	v_lshlrev_b32_e32 v110, 16, v49
	v_and_b32_e32 v111, 0xffff0000, v49
	v_pk_mul_f32 v[112:113], v[112:113], v[108:109]
	v_pk_mul_f32 v[114:115], v[114:115], v[110:111]
	v_lshlrev_b32_e32 v108, 16, v56
	v_and_b32_e32 v109, 0xffff0000, v56
	v_lshlrev_b32_e32 v110, 16, v57
	v_and_b32_e32 v111, 0xffff0000, v57
	v_pk_mul_f32 v[114:115], v[114:115], v[110:111]
	v_pk_mul_f32 v[112:113], v[112:113], v[108:109]
	s_nop 0
	v_cvt_pk_bf16_f32 v116, v112, v113
	v_cvt_pk_bf16_f32 v117, v114, v115
	global_load_dwordx2 v[48:49], v104, s[0:1]
	global_load_dwordx2 v[50:51], v104, s[2:3]
	global_load_dwordx2 v[52:53], v104, s[2:3] offset:-512
	global_load_dwordx2 v[54:55], v104, s[2:3] offset:-1024
	global_load_dwordx2 v[56:57], v105, s[18:19]
	v_add_u32_e32 v104, 0x4000, v104
	v_add_u32_e32 v105, 0x10000, v105
	global_store_dwordx2 v106, v[116:117], s[20:21]
	v_add_u32_e32 v106, 0x10000, v106
	s_waitcnt vmcnt(16)
	v_lshlrev_b32_e32 v108, 16, v64
	v_and_b32_e32 v109, 0xffff0000, v64
	v_lshlrev_b32_e32 v110, 16, v65
	v_and_b32_e32 v111, 0xffff0000, v65
	v_pk_mul_f32 v[114:115], v[38:39], v[110:111]
	v_pk_mul_f32 v[112:113], v[36:37], v[108:109]
	v_lshlrev_b32_e32 v108, 16, v62
	v_and_b32_e32 v109, 0xffff0000, v62
	v_lshlrev_b32_e32 v110, 16, v63
	v_and_b32_e32 v111, 0xffff0000, v63
	v_pk_fma_f32 v[112:113], v[40:41], v[108:109], v[112:113]
	v_pk_fma_f32 v[114:115], v[42:43], v[110:111], v[114:115]
	v_lshlrev_b32_e32 v108, 16, v60
	v_and_b32_e32 v109, 0xffff0000, v60
	v_lshlrev_b32_e32 v110, 16, v61
	v_and_b32_e32 v111, 0xffff0000, v61
	v_pk_fma_f32 v[114:115], v[46:47], v[110:111], v[114:115]
	v_pk_fma_f32 v[112:113], v[44:45], v[108:109], v[112:113]
	v_lshlrev_b32_e32 v108, 16, v58
	v_and_b32_e32 v109, 0xffff0000, v58
	v_lshlrev_b32_e32 v110, 16, v59
	v_and_b32_e32 v111, 0xffff0000, v59
	v_pk_mul_f32 v[112:113], v[112:113], v[108:109]
	v_pk_mul_f32 v[114:115], v[114:115], v[110:111]
	v_lshlrev_b32_e32 v108, 16, v66
	v_and_b32_e32 v109, 0xffff0000, v66
	v_lshlrev_b32_e32 v110, 16, v67
	v_and_b32_e32 v111, 0xffff0000, v67
	v_pk_mul_f32 v[114:115], v[114:115], v[110:111]
	v_pk_mul_f32 v[112:113], v[112:113], v[108:109]
	s_nop 0
	v_cvt_pk_bf16_f32 v116, v112, v113
	v_cvt_pk_bf16_f32 v117, v114, v115
	global_load_dwordx2 v[58:59], v104, s[0:1]
	global_load_dwordx2 v[60:61], v104, s[2:3]
	global_load_dwordx2 v[62:63], v104, s[2:3] offset:-512
	global_load_dwordx2 v[64:65], v104, s[2:3] offset:-1024
	global_load_dwordx2 v[66:67], v105, s[18:19]
	v_add_u32_e32 v104, 0x4000, v104
	v_add_u32_e32 v105, 0x10000, v105
	global_store_dwordx2 v106, v[116:117], s[20:21]
	v_add_u32_e32 v106, 0x10000, v106
	s_waitcnt vmcnt(17)
	v_lshlrev_b32_e32 v108, 16, v90
	v_and_b32_e32 v109, 0xffff0000, v90
	v_lshlrev_b32_e32 v110, 16, v91
	v_and_b32_e32 v111, 0xffff0000, v91
	v_pk_mul_f32 v[114:115], v[38:39], v[110:111]
	v_pk_mul_f32 v[112:113], v[36:37], v[108:109]
	v_lshlrev_b32_e32 v108, 16, v88
	v_and_b32_e32 v109, 0xffff0000, v88
	v_lshlrev_b32_e32 v110, 16, v89
	v_and_b32_e32 v111, 0xffff0000, v89
	v_pk_fma_f32 v[112:113], v[40:41], v[108:109], v[112:113]
	v_pk_fma_f32 v[114:115], v[42:43], v[110:111], v[114:115]
	v_lshlrev_b32_e32 v108, 16, v86
	v_and_b32_e32 v109, 0xffff0000, v86
	v_lshlrev_b32_e32 v110, 16, v87
	v_and_b32_e32 v111, 0xffff0000, v87
	v_pk_fma_f32 v[114:115], v[46:47], v[110:111], v[114:115]
	v_pk_fma_f32 v[112:113], v[44:45], v[108:109], v[112:113]
	v_lshlrev_b32_e32 v108, 16, v84
	v_and_b32_e32 v109, 0xffff0000, v84
	v_lshlrev_b32_e32 v110, 16, v85
	v_and_b32_e32 v111, 0xffff0000, v85
	v_pk_mul_f32 v[112:113], v[112:113], v[108:109]
	v_pk_mul_f32 v[114:115], v[114:115], v[110:111]
	v_lshlrev_b32_e32 v108, 16, v92
	v_and_b32_e32 v109, 0xffff0000, v92
	v_lshlrev_b32_e32 v110, 16, v93
	v_and_b32_e32 v111, 0xffff0000, v93
	v_pk_mul_f32 v[114:115], v[114:115], v[110:111]
	v_pk_mul_f32 v[112:113], v[112:113], v[108:109]
	s_nop 0
	v_cvt_pk_bf16_f32 v116, v112, v113
	v_cvt_pk_bf16_f32 v117, v114, v115
	global_load_dwordx2 v[84:85], v104, s[0:1]
	global_load_dwordx2 v[86:87], v104, s[2:3]
	global_load_dwordx2 v[88:89], v104, s[2:3] offset:-512
	global_load_dwordx2 v[90:91], v104, s[2:3] offset:-1024
	global_load_dwordx2 v[92:93], v105, s[18:19]
	v_add_u32_e32 v104, 0x4000, v104
	v_add_u32_e32 v105, 0x10000, v105
	global_store_dwordx2 v106, v[116:117], s[20:21]
	v_add_u32_e32 v106, 0x10000, v106
	s_waitcnt vmcnt(18)
; DI v2u pack4(f32x4 a) { v2u w; w.x = cvtpk(a[0], a[1]); w.y = cvtpk(a[2], a[3]); return w; }
; DI f32x4 unpack4(v2u w) { return (f32x4){bflo(w.x), bfhi(w.x), bflo(w.y), bfhi(w.y)}; }
; DI void unit_memattn(int u, const bf16* __restrict__ MQ, const bf16* __restrict__ MK, const bf16* __restrict__ MV, const bf16* __restrict__ G, bf16* __restrict__ MIX, const bf16* __restrict__ CB, const bf16* __restrict__ U, const float* __restrict__ convw, ...
;     ...
;         for (int rl = tid >> 4; rl < 256; rl += NT / 16) { const size_t r2 = (size_t)b * SEQ + qb * 256 + rl; const int t = (int)(r2 & (SEQ - 1));
;             const f32x4 cb = unpack4(*(const v2u*)(CB + r2 * 256 + c4)), u0 = unpack4(*(const v2u*)(U + r2 * 256 + c4));
;             f32x4 u1 = (f32x4){0.f, 0.f, 0.f, 0.f}, u2 = u1;
;             if (t >= 1) u1 = unpack4(*(const v2u*)(U + (r2 - 1) * 256 + c4));
;             if (t >= 2) u2 = unpack4(*(const v2u*)(U + (r2 - 2) * 256 + c4));
;             const f32x4 gg = unpack4(*(const v2u*)(G + r2 * D + c4));
;             *(v2u*)(MIX + r2 * D + c4) = pack4(cb * (w0 * u2 + w1 * u1 + w2 * u0) * gg); }
	v_lshlrev_b32_e32 v108, 16, v100
	v_and_b32_e32 v109, 0xffff0000, v100
	v_lshlrev_b32_e32 v110, 16, v101
	v_and_b32_e32 v111, 0xffff0000, v101
	v_pk_mul_f32 v[114:115], v[38:39], v[110:111]
	v_pk_mul_f32 v[112:113], v[36:37], v[108:109]
	v_lshlrev_b32_e32 v108, 16, v98
	v_and_b32_e32 v109, 0xffff0000, v98
	v_lshlrev_b32_e32 v110, 16, v99
	v_and_b32_e32 v111, 0xffff0000, v99
	v_pk_fma_f32 v[112:113], v[40:41], v[108:109], v[112:113]
	v_pk_fma_f32 v[114:115], v[42:43], v[110:111], v[114:115]
	v_lshlrev_b32_e32 v108, 16, v96
	v_and_b32_e32 v109, 0xffff0000, v96
	v_lshlrev_b32_e32 v110, 16, v97
	v_and_b32_e32 v111, 0xffff0000, v97
	v_pk_fma_f32 v[114:115], v[46:47], v[110:111], v[114:115]
	v_pk_fma_f32 v[112:113], v[44:45], v[108:109], v[112:113]
	v_lshlrev_b32_e32 v108, 16, v94
	v_and_b32_e32 v109, 0xffff0000, v94
	v_lshlrev_b32_e32 v110, 16, v95
	v_and_b32_e32 v111, 0xffff0000, v95
	v_pk_mul_f32 v[112:113], v[112:113], v[108:109]
	v_pk_mul_f32 v[114:115], v[114:115], v[110:111]
	v_lshlrev_b32_e32 v108, 16, v102
	v_and_b32_e32 v109, 0xffff0000, v102
	v_lshlrev_b32_e32 v110, 16, v103
	v_and_b32_e32 v111, 0xffff0000, v103
	v_pk_mul_f32 v[114:115], v[114:115], v[110:111]
	v_pk_mul_f32 v[112:113], v[112:113], v[108:109]
	s_nop 0
	v_cvt_pk_bf16_f32 v116, v112, v113
	v_cvt_pk_bf16_f32 v117, v114, v115
	global_load_dwordx2 v[94:95], v104, s[0:1]
	global_load_dwordx2 v[96:97], v104, s[2:3]
	global_load_dwordx2 v[98:99], v104, s[2:3] offset:-512
	global_load_dwordx2 v[100:101], v104, s[2:3] offset:-1024
	global_load_dwordx2 v[102:103], v105, s[18:19]
	global_store_dwordx2 v106, v[116:117], s[20:21]
	v_add_u32_e32 v106, 0x10000, v106
	s_waitcnt vmcnt(19)
	v_lshlrev_b32_e32 v108, 16, v54
	v_and_b32_e32 v109, 0xffff0000, v54
	v_lshlrev_b32_e32 v110, 16, v55
	v_and_b32_e32 v111, 0xffff0000, v55
	v_pk_mul_f32 v[114:115], v[38:39], v[110:111]
	v_pk_mul_f32 v[112:113], v[36:37], v[108:109]
	v_lshlrev_b32_e32 v108, 16, v52
	v_and_b32_e32 v109, 0xffff0000, v52
	v_lshlrev_b32_e32 v110, 16, v53
	v_and_b32_e32 v111, 0xffff0000, v53
	v_pk_fma_f32 v[112:113], v[40:41], v[108:109], v[112:113]
	v_pk_fma_f32 v[114:115], v[42:43], v[110:111], v[114:115]
	v_lshlrev_b32_e32 v108, 16, v50
	v_and_b32_e32 v109, 0xffff0000, v50
	v_lshlrev_b32_e32 v110, 16, v51
	v_and_b32_e32 v111, 0xffff0000, v51
	v_pk_fma_f32 v[114:115], v[46:47], v[110:111], v[114:115]
	v_pk_fma_f32 v[112:113], v[44:45], v[108:109], v[112:113]
	v_lshlrev_b32_e32 v108, 16, v48
	v_and_b32_e32 v109, 0xffff0000, v48
	v_lshlrev_b32_e32 v110, 16, v49
	v_and_b32_e32 v111, 0xffff0000, v49
	v_pk_mul_f32 v[112:113], v[112:113], v[108:109]
	v_pk_mul_f32 v[114:115], v[114:115], v[110:111]
	v_lshlrev_b32_e32 v108, 16, v56
	v_and_b32_e32 v109, 0xffff0000, v56
	v_lshlrev_b32_e32 v110, 16, v57
	v_and_b32_e32 v111, 0xffff0000, v57
	v_pk_mul_f32 v[114:115], v[114:115], v[110:111]
	v_pk_mul_f32 v[112:113], v[112:113], v[108:109]
	s_nop 0
	v_cvt_pk_bf16_f32 v116, v112, v113
	v_cvt_pk_bf16_f32 v117, v114, v115
	global_store_dwordx2 v106, v[116:117], s[20:21]
	v_add_u32_e32 v106, 0x10000, v106
	s_waitcnt vmcnt(14)
; DI v2u pack4(f32x4 a) { v2u w; w.x = cvtpk(a[0], a[1]); w.y = cvtpk(a[2], a[3]); return w; }
; DI f32x4 unpack4(v2u w) { return (f32x4){bflo(w.x), bfhi(w.x), bflo(w.y), bfhi(w.y)}; }
; DI void unit_memattn(int u, const bf16* __restrict__ MQ, const bf16* __restrict__ MK, const bf16* __restrict__ MV, const bf16* __restrict__ G, bf16* __restrict__ MIX, const bf16* __restrict__ CB, const bf16* __restrict__ U, const float* __restrict__ convw, ...
;     ...
;         for (int rl = tid >> 4; rl < 256; rl += NT / 16) { const size_t r2 = (size_t)b * SEQ + qb * 256 + rl; const int t = (int)(r2 & (SEQ - 1));
;             const f32x4 cb = unpack4(*(const v2u*)(CB + r2 * 256 + c4)), u0 = unpack4(*(const v2u*)(U + r2 * 256 + c4));
;             f32x4 u1 = (f32x4){0.f, 0.f, 0.f, 0.f}, u2 = u1;
;             if (t >= 1) u1 = unpack4(*(const v2u*)(U + (r2 - 1) * 256 + c4));
;             if (t >= 2) u2 = unpack4(*(const v2u*)(U + (r2 - 2) * 256 + c4));
;             const f32x4 gg = unpack4(*(const v2u*)(G + r2 * D + c4));
;             *(v2u*)(MIX + r2 * D + c4) = pack4(cb * (w0 * u2 + w1 * u1 + w2 * u0) * gg); }
	v_lshlrev_b32_e32 v108, 16, v64
	v_and_b32_e32 v109, 0xffff0000, v64
	v_lshlrev_b32_e32 v110, 16, v65
	v_and_b32_e32 v111, 0xffff0000, v65
	v_pk_mul_f32 v[114:115], v[38:39], v[110:111]
	v_pk_mul_f32 v[112:113], v[36:37], v[108:109]
	v_lshlrev_b32_e32 v108, 16, v62
	v_and_b32_e32 v109, 0xffff0000, v62
	v_lshlrev_b32_e32 v110, 16, v63
	v_and_b32_e32 v111, 0xffff0000, v63
	v_pk_fma_f32 v[112:113], v[40:41], v[108:109], v[112:113]
	v_pk_fma_f32 v[114:115], v[42:43], v[110:111], v[114:115]
	v_lshlrev_b32_e32 v108, 16, v60
	v_and_b32_e32 v109, 0xffff0000, v60
	v_lshlrev_b32_e32 v110, 16, v61
	v_and_b32_e32 v111, 0xffff0000, v61
	v_pk_fma_f32 v[114:115], v[46:47], v[110:111], v[114:115]
	v_pk_fma_f32 v[112:113], v[44:45], v[108:109], v[112:113]
	v_lshlrev_b32_e32 v108, 16, v58
	v_and_b32_e32 v109, 0xffff0000, v58
	v_lshlrev_b32_e32 v110, 16, v59
	v_and_b32_e32 v111, 0xffff0000, v59
	v_pk_mul_f32 v[112:113], v[112:113], v[108:109]
	v_pk_mul_f32 v[114:115], v[114:115], v[110:111]
	v_lshlrev_b32_e32 v108, 16, v66
	v_and_b32_e32 v109, 0xffff0000, v66
	v_lshlrev_b32_e32 v110, 16, v67
	v_and_b32_e32 v111, 0xffff0000, v67
	v_pk_mul_f32 v[114:115], v[114:115], v[110:111]
	v_pk_mul_f32 v[112:113], v[112:113], v[108:109]
	s_nop 0
	v_cvt_pk_bf16_f32 v116, v112, v113
	v_cvt_pk_bf16_f32 v117, v114, v115
	global_store_dwordx2 v106, v[116:117], s[20:21]
	v_add_u32_e32 v106, 0x10000, v106
	s_waitcnt vmcnt(9)
	v_lshlrev_b32_e32 v108, 16, v90
	v_and_b32_e32 v109, 0xffff0000, v90
	v_lshlrev_b32_e32 v110, 16, v91
	v_and_b32_e32 v111, 0xffff0000, v91
	v_pk_mul_f32 v[114:115], v[38:39], v[110:111]
	v_pk_mul_f32 v[112:113], v[36:37], v[108:109]
	v_lshlrev_b32_e32 v108, 16, v88
	v_and_b32_e32 v109, 0xffff0000, v88
	v_lshlrev_b32_e32 v110, 16, v89
	v_and_b32_e32 v111, 0xffff0000, v89
	v_pk_fma_f32 v[112:113], v[40:41], v[108:109], v[112:113]
	v_pk_fma_f32 v[114:115], v[42:43], v[110:111], v[114:115]
	v_lshlrev_b32_e32 v108, 16, v86
	v_and_b32_e32 v109, 0xffff0000, v86
	v_lshlrev_b32_e32 v110, 16, v87
	v_and_b32_e32 v111, 0xffff0000, v87
	v_pk_fma_f32 v[114:115], v[46:47], v[110:111], v[114:115]
	v_pk_fma_f32 v[112:113], v[44:45], v[108:109], v[112:113]
	v_lshlrev_b32_e32 v108, 16, v84
	v_and_b32_e32 v109, 0xffff0000, v84
	v_lshlrev_b32_e32 v110, 16, v85
	v_and_b32_e32 v111, 0xffff0000, v85
	v_pk_mul_f32 v[112:113], v[112:113], v[108:109]
	v_pk_mul_f32 v[114:115], v[114:115], v[110:111]
	v_lshlrev_b32_e32 v108, 16, v92
	v_and_b32_e32 v109, 0xffff0000, v92
	v_lshlrev_b32_e32 v110, 16, v93
	v_and_b32_e32 v111, 0xffff0000, v93
	v_pk_mul_f32 v[114:115], v[114:115], v[110:111]
	v_pk_mul_f32 v[112:113], v[112:113], v[108:109]
	s_nop 0
	v_cvt_pk_bf16_f32 v116, v112, v113
	v_cvt_pk_bf16_f32 v117, v114, v115
	global_store_dwordx2 v106, v[116:117], s[20:21]
	v_add_u32_e32 v106, 0x10000, v106
	s_waitcnt vmcnt(4)
	v_lshlrev_b32_e32 v108, 16, v100
	v_and_b32_e32 v109, 0xffff0000, v100
	v_lshlrev_b32_e32 v110, 16, v101
	v_and_b32_e32 v111, 0xffff0000, v101
	v_pk_mul_f32 v[114:115], v[38:39], v[110:111]
	v_pk_mul_f32 v[112:113], v[36:37], v[108:109]
	v_lshlrev_b32_e32 v108, 16, v98
	v_and_b32_e32 v109, 0xffff0000, v98
	v_lshlrev_b32_e32 v110, 16, v99
	v_and_b32_e32 v111, 0xffff0000, v99
	v_pk_fma_f32 v[112:113], v[40:41], v[108:109], v[112:113]
	v_pk_fma_f32 v[114:115], v[42:43], v[110:111], v[114:115]
	v_lshlrev_b32_e32 v108, 16, v96
	v_and_b32_e32 v109, 0xffff0000, v96
	v_lshlrev_b32_e32 v110, 16, v97
	v_and_b32_e32 v111, 0xffff0000, v97
	v_pk_fma_f32 v[114:115], v[46:47], v[110:111], v[114:115]
	v_pk_fma_f32 v[112:113], v[44:45], v[108:109], v[112:113]
	v_lshlrev_b32_e32 v108, 16, v94
	v_and_b32_e32 v109, 0xffff0000, v94
	v_lshlrev_b32_e32 v110, 16, v95
	v_and_b32_e32 v111, 0xffff0000, v95
	v_pk_mul_f32 v[112:113], v[112:113], v[108:109]
	v_pk_mul_f32 v[114:115], v[114:115], v[110:111]
	v_lshlrev_b32_e32 v108, 16, v102
	v_and_b32_e32 v109, 0xffff0000, v102
	v_lshlrev_b32_e32 v110, 16, v103
	v_and_b32_e32 v111, 0xffff0000, v103
	v_pk_mul_f32 v[114:115], v[114:115], v[110:111]
	v_pk_mul_f32 v[112:113], v[112:113], v[108:109]
	s_nop 0
	v_cvt_pk_bf16_f32 v116, v112, v113
	v_cvt_pk_bf16_f32 v117, v114, v115
	global_store_dwordx2 v106, v[116:117], s[20:21]
